# ssd dt/cumsum tile: softplus for all 384 values in parallel (branch-free, same arithmetic), 12 lanes run the 32-step cumsum from registers
# speedup vs baseline: 1.0314x; 1.0314x over previous
; __device__ __forceinline__ float bf2f(bf16_t v) { return __uint_as_float(((unsigned)v) << 16); }
; __device__ __forceinline__ int launder(int x) { asm volatile("" : "+v"(x)); return x; }
; __device__ __forceinline__ void ssd_dtcum_tile(const Params& p, int l, int tile, unsigned char* smem) {
;   const int b = tile / 136, c32 = tile % 136, p0 = c32 * 32;
;   float* draw = (float*)smem;
;   const int tid = launder(threadIdx.x);
;   for (int q = tid; q < 384; q += 256) {
;     const int i = q / 12, dh = q % 12;
;     draw[q] = bf2f(p.PS[((size_t)b * TPB + p0 + i) * 912 + 896 + dh]);
;   }
;   __syncthreads();
.LBB0_597:
	s_cmpk_gt_i32 s47, 0x43f
	s_mov_b64 s[42:43], -1
	s_cbranch_scc0 .LBB0_814
	s_cmpk_gt_u32 s47, 0x63f
	s_cbranch_scc0 .LBB0_802
	s_sub_i32 s28, s47, 0x640
	s_mul_i32 s42, s28, 0xf0f1
	s_lshr_b32 s63, s42, 23
	s_mul_i32 s42, s63, 0x88
	s_sub_i32 s28, s28, s42
	s_lshl_b32 s62, s28, 5
	s_mul_i32 s42, s63, 0x1100
	s_add_i32 s62, s42, s62
	v_mov_b32_e32 v0, v189
	v_readlane_b32 s14, v251, 62
	v_readlane_b32 s15, v251, 63
	v_readlane_b32 s78, v251, 30
	v_readlane_b32 s79, v251, 31
	v_readlane_b32 s76, v251, 28
	v_readlane_b32 s77, v251, 29
	v_readlane_b32 s8, v252, 8
	v_readlane_b32 s9, v252, 9
	s_mul_i32 s63, s46, 6
	s_mov_b32 s0, 0xaaab
	s_mov_b32 s3, 0x41700000
	s_mov_b32 s4, 0x3c23d70a
	s_mov_b32 s5, 0x800000
	s_mov_b32 s6, 0x3f317217
	s_mov_b32 s7, 0x7f800000
	s_mov_b32 s10, 0xbeaaaaab
	v_mul_u32_u24_e32 v1, s0, v0
	v_lshrrev_b32_e32 v1, 19, v1
	v_mul_u32_u24_e32 v2, 12, v1
	v_sub_u32_e32 v2, v0, v2
	v_add_u32_e32 v3, s62, v1
	v_mul_u32_u24_e32 v3, s39, v3
	v_lshl_add_u32 v3, v2, 1, v3
	v_add_u32_e32 v4, s63, v2
	v_lshlrev_b32_e32 v4, 2, v4
	global_load_ushort v10, v3, s[14:15] offset:1792
	global_load_dword v12, v4, s[78:79]
	v_min_u32_e32 v5, 11, v0
	v_add_u32_e32 v5, s63, v5
	v_lshlrev_b32_e32 v5, 2, v5
	global_load_dword v14, v5, s[76:77]
	v_add_u32_e32 v6, 0x100, v0
	v_mul_u32_u24_e32 v1, s0, v6
	v_lshrrev_b32_e32 v1, 19, v1
	v_mul_u32_u24_e32 v2, 12, v1
	v_sub_u32_e32 v2, v6, v2
	v_add_u32_e32 v7, s62, v1
	v_mul_u32_u24_e32 v7, s39, v7
	v_lshl_add_u32 v7, v2, 1, v7
	v_add_u32_e32 v8, s63, v2
	v_lshlrev_b32_e32 v8, 2, v8
	v_mov_b32_e32 v11, v164
	v_mov_b32_e32 v13, v164
	v_cmp_gt_u32_e32 vcc, 0x80, v0
	s_and_saveexec_b64 s[56:57], vcc
	global_load_ushort v11, v7, s[14:15] offset:1792
	global_load_dword v13, v8, s[78:79]
	s_mov_b64 exec, s[56:57]
	v_lshlrev_b32_e32 v15, 2, v0
	s_waitcnt vmcnt(0)
	v_lshlrev_b32_e32 v10, 16, v10
	v_add_f32_e32 v10, v12, v10
	v_lshlrev_b32_e32 v11, 16, v11
	v_add_f32_e32 v11, v13, v11
	v_mul_f32_e32 v20, 0x3fb8aa3b, v10
	v_exp_f32_e32 v20, v20
	v_cmp_nlt_f32_e64 s[42:43], s3, v10
	v_add_f32_e32 v21, 1.0, v20
	v_cmp_ngt_f32_e64 s[58:59], s4, v20
	v_cmp_gt_f32_e64 s[60:61], s5, v21
	s_nop 1
	v_cndmask_b32_e64 v22, 0, 32, s[60:61]
	v_ldexp_f32 v21, v21, v22
	v_log_f32_e32 v21, v21
	s_nop 0
	v_mul_f32_e32 v22, 0x3f317217, v21
	v_fma_f32 v22, v21, s6, -v22
	v_fmac_f32_e32 v22, 0x3377d1cf, v21
	v_fmac_f32_e32 v22, 0x3f317217, v21
	v_cmp_lt_f32_e64 s[12:13], |v21|, s7
	s_nop 1
	v_cndmask_b32_e64 v21, v21, v22, s[12:13]
	v_cndmask_b32_e64 v22, 0, v206, s[60:61]
	v_sub_f32_e32 v21, v21, v22
	v_fma_f32 v22, v20, s10, 0.5
	v_fma_f32 v22, -v20, v22, 1.0
	v_mul_f32_e32 v22, v20, v22
	v_cndmask_b32_e64 v21, v22, v21, s[58:59]
	v_cndmask_b32_e64 v10, v10, v21, s[42:43]
	v_mul_f32_e32 v20, 0x3fb8aa3b, v11
	v_exp_f32_e32 v20, v20
	v_cmp_nlt_f32_e64 s[42:43], s3, v11
	v_add_f32_e32 v21, 1.0, v20
	v_cmp_ngt_f32_e64 s[58:59], s4, v20
	v_cmp_gt_f32_e64 s[60:61], s5, v21
	s_nop 1
	v_cndmask_b32_e64 v22, 0, 32, s[60:61]
	v_ldexp_f32 v21, v21, v22
	v_log_f32_e32 v21, v21
	s_nop 0
	v_mul_f32_e32 v22, 0x3f317217, v21
	v_fma_f32 v22, v21, s6, -v22
	v_fmac_f32_e32 v22, 0x3377d1cf, v21
	v_fmac_f32_e32 v22, 0x3f317217, v21
	v_cmp_lt_f32_e64 s[12:13], |v21|, s7
	s_nop 1
	v_cndmask_b32_e64 v21, v21, v22, s[12:13]
	v_cndmask_b32_e64 v22, 0, v206, s[60:61]
	v_sub_f32_e32 v21, v21, v22
	v_fma_f32 v22, v20, s10, 0.5
	v_fma_f32 v22, -v20, v22, 1.0
	v_mul_f32_e32 v22, v20, v22
	v_cndmask_b32_e64 v21, v22, v21, s[58:59]
	v_cndmask_b32_e64 v11, v11, v21, s[42:43]
	s_lshl_b32 s62, s62, 3
	s_mov_b32 s28, 0x22000
	ds_write_b32 v15, v10
	v_cmp_gt_u32_e32 vcc, 0x80, v0
	s_and_saveexec_b64 s[56:57], vcc
	ds_write_b32 v15, v11 offset:1024
	s_mov_b64 exec, s[56:57]
	s_waitcnt lgkmcnt(0)
	s_barrier
	v_readlane_b32 s0, v251, 48
	v_readlane_b32 s1, v251, 49
	v_readlane_b32 s2, v251, 50
	v_readlane_b32 s3, v251, 51
	v_readlane_b32 s4, v251, 52
	v_readlane_b32 s5, v251, 53
	v_readlane_b32 s6, v251, 54
	v_readlane_b32 s7, v251, 55
	v_readlane_b32 s10, v251, 58
	v_readlane_b32 s11, v251, 59
	v_readlane_b32 s12, v251, 60
	v_readlane_b32 s13, v251, 61
	v_cmp_gt_u32_e32 vcc, 12, v0
	s_and_saveexec_b64 s[56:57], vcc
	s_cbranch_execz .LBB0_801
; __device__ __forceinline__ void ssd_dtcum_tile(const Params& p, int l, int tile, unsigned char* smem) {
;     ...
;   if (tid < 12) {
;     const int dh = tid, d = dh / 6, h = dh % 6;
;     const float a_neg = -__expf(p.ssm_a_log[(l * 2 + d) * 6 + h]);
;     const float bias = p.ssm_dt_bias[(l * 2 + d) * 6 + h];
;     float cum = 0.f;
;     for (int k = 0; k < 32; ++k) {
;       const int it = (d == 0) ? k : 31 - k;
;       const float dt = softplusf_(draw[it * 12 + dh] + bias);
;       cum += dt * a_neg;
;       p.DTC[(size_t)dh * TOK + (size_t)b * TPB + p0 + it] = make_float2(dt, cum);
;     }
;   }
	ds_read_b32 v32, v15
	ds_read_b32 v33, v15 offset:48
	ds_read_b32 v34, v15 offset:96
	ds_read_b32 v35, v15 offset:144
	ds_read_b32 v36, v15 offset:192
	ds_read_b32 v37, v15 offset:240
	ds_read_b32 v38, v15 offset:288
	ds_read_b32 v39, v15 offset:336
	ds_read_b32 v40, v15 offset:384
	ds_read_b32 v41, v15 offset:432
	ds_read_b32 v42, v15 offset:480
	ds_read_b32 v43, v15 offset:528
	ds_read_b32 v44, v15 offset:576
	ds_read_b32 v45, v15 offset:624
	ds_read_b32 v46, v15 offset:672
	ds_read_b32 v47, v15 offset:720
	ds_read_b32 v48, v15 offset:768
	ds_read_b32 v49, v15 offset:816
	ds_read_b32 v50, v15 offset:864
	ds_read_b32 v51, v15 offset:912
	ds_read_b32 v52, v15 offset:960
	ds_read_b32 v53, v15 offset:1008
	ds_read_b32 v54, v15 offset:1056
	ds_read_b32 v55, v15 offset:1104
	ds_read_b32 v56, v15 offset:1152
	ds_read_b32 v57, v15 offset:1200
	ds_read_b32 v58, v15 offset:1248
	ds_read_b32 v59, v15 offset:1296
	ds_read_b32 v60, v15 offset:1344
	ds_read_b32 v61, v15 offset:1392
	ds_read_b32 v62, v15 offset:1440
	ds_read_b32 v63, v15 offset:1488
	v_mul_f32_e32 v14, 0x3fb8aa3b, v14
	v_exp_f32_e32 v5, v14
	v_cmp_gt_u32_e32 vcc, 6, v0
	v_mul_u32_u24_e32 v16, s28, v0
	v_add_u32_e32 v16, s62, v16
	v_mov_b32_e32 v18, 0xf8
	v_mov_b32_e32 v19, 8
	v_mov_b32_e32 v20, -8
	v_cndmask_b32_e32 v17, v18, v164, vcc
	v_cndmask_b32_e32 v19, v20, v19, vcc
	v_add_u32_e32 v16, v16, v17
	s_waitcnt lgkmcnt(0)
	v_cndmask_b32_e32 v2, v63, v32, vcc
	v_fma_f32 v3, -v5, v2, 0
	global_store_dwordx2 v16, v[2:3], s[8:9]
	v_add_u32_e32 v16, v16, v19
	v_cndmask_b32_e32 v2, v62, v33, vcc
	v_fma_f32 v3, -v5, v2, v3
	global_store_dwordx2 v16, v[2:3], s[8:9]
	v_add_u32_e32 v16, v16, v19
	v_cndmask_b32_e32 v2, v61, v34, vcc
	v_fma_f32 v3, -v5, v2, v3
	global_store_dwordx2 v16, v[2:3], s[8:9]
	v_add_u32_e32 v16, v16, v19
	v_cndmask_b32_e32 v2, v60, v35, vcc
	v_fma_f32 v3, -v5, v2, v3
	global_store_dwordx2 v16, v[2:3], s[8:9]
	v_add_u32_e32 v16, v16, v19
	v_cndmask_b32_e32 v2, v59, v36, vcc
	v_fma_f32 v3, -v5, v2, v3
	global_store_dwordx2 v16, v[2:3], s[8:9]
	v_add_u32_e32 v16, v16, v19
	v_cndmask_b32_e32 v2, v58, v37, vcc
	v_fma_f32 v3, -v5, v2, v3
	global_store_dwordx2 v16, v[2:3], s[8:9]
	v_add_u32_e32 v16, v16, v19
	v_cndmask_b32_e32 v2, v57, v38, vcc
	v_fma_f32 v3, -v5, v2, v3
	global_store_dwordx2 v16, v[2:3], s[8:9]
	v_add_u32_e32 v16, v16, v19
	v_cndmask_b32_e32 v2, v56, v39, vcc
	v_fma_f32 v3, -v5, v2, v3
	global_store_dwordx2 v16, v[2:3], s[8:9]
	v_add_u32_e32 v16, v16, v19
	v_cndmask_b32_e32 v2, v55, v40, vcc
	v_fma_f32 v3, -v5, v2, v3
	global_store_dwordx2 v16, v[2:3], s[8:9]
	v_add_u32_e32 v16, v16, v19
	v_cndmask_b32_e32 v2, v54, v41, vcc
	v_fma_f32 v3, -v5, v2, v3
	global_store_dwordx2 v16, v[2:3], s[8:9]
	v_add_u32_e32 v16, v16, v19
	v_cndmask_b32_e32 v2, v53, v42, vcc
	v_fma_f32 v3, -v5, v2, v3
	global_store_dwordx2 v16, v[2:3], s[8:9]
	v_add_u32_e32 v16, v16, v19
	v_cndmask_b32_e32 v2, v52, v43, vcc
	v_fma_f32 v3, -v5, v2, v3
	global_store_dwordx2 v16, v[2:3], s[8:9]
	v_add_u32_e32 v16, v16, v19
	v_cndmask_b32_e32 v2, v51, v44, vcc
	v_fma_f32 v3, -v5, v2, v3
	global_store_dwordx2 v16, v[2:3], s[8:9]
	v_add_u32_e32 v16, v16, v19
	v_cndmask_b32_e32 v2, v50, v45, vcc
	v_fma_f32 v3, -v5, v2, v3
	global_store_dwordx2 v16, v[2:3], s[8:9]
	v_add_u32_e32 v16, v16, v19
	v_cndmask_b32_e32 v2, v49, v46, vcc
	v_fma_f32 v3, -v5, v2, v3
	global_store_dwordx2 v16, v[2:3], s[8:9]
	v_add_u32_e32 v16, v16, v19
	v_cndmask_b32_e32 v2, v48, v47, vcc
	v_fma_f32 v3, -v5, v2, v3
	global_store_dwordx2 v16, v[2:3], s[8:9]
	v_add_u32_e32 v16, v16, v19
	v_cndmask_b32_e32 v2, v47, v48, vcc
	v_fma_f32 v3, -v5, v2, v3
	global_store_dwordx2 v16, v[2:3], s[8:9]
	v_add_u32_e32 v16, v16, v19
	v_cndmask_b32_e32 v2, v46, v49, vcc
	v_fma_f32 v3, -v5, v2, v3
	global_store_dwordx2 v16, v[2:3], s[8:9]
	v_add_u32_e32 v16, v16, v19
	v_cndmask_b32_e32 v2, v45, v50, vcc
	v_fma_f32 v3, -v5, v2, v3
	global_store_dwordx2 v16, v[2:3], s[8:9]
	v_add_u32_e32 v16, v16, v19
	v_cndmask_b32_e32 v2, v44, v51, vcc
	v_fma_f32 v3, -v5, v2, v3
	global_store_dwordx2 v16, v[2:3], s[8:9]
	v_add_u32_e32 v16, v16, v19
	v_cndmask_b32_e32 v2, v43, v52, vcc
	v_fma_f32 v3, -v5, v2, v3
	global_store_dwordx2 v16, v[2:3], s[8:9]
	v_add_u32_e32 v16, v16, v19
	v_cndmask_b32_e32 v2, v42, v53, vcc
	v_fma_f32 v3, -v5, v2, v3
	global_store_dwordx2 v16, v[2:3], s[8:9]
	v_add_u32_e32 v16, v16, v19
	v_cndmask_b32_e32 v2, v41, v54, vcc
	v_fma_f32 v3, -v5, v2, v3
	global_store_dwordx2 v16, v[2:3], s[8:9]
	v_add_u32_e32 v16, v16, v19
	v_cndmask_b32_e32 v2, v40, v55, vcc
	v_fma_f32 v3, -v5, v2, v3
	global_store_dwordx2 v16, v[2:3], s[8:9]
	v_add_u32_e32 v16, v16, v19
	v_cndmask_b32_e32 v2, v39, v56, vcc
	v_fma_f32 v3, -v5, v2, v3
	global_store_dwordx2 v16, v[2:3], s[8:9]
	v_add_u32_e32 v16, v16, v19
	v_cndmask_b32_e32 v2, v38, v57, vcc
	v_fma_f32 v3, -v5, v2, v3
	global_store_dwordx2 v16, v[2:3], s[8:9]
	v_add_u32_e32 v16, v16, v19
	v_cndmask_b32_e32 v2, v37, v58, vcc
	v_fma_f32 v3, -v5, v2, v3
	global_store_dwordx2 v16, v[2:3], s[8:9]
	v_add_u32_e32 v16, v16, v19
	v_cndmask_b32_e32 v2, v36, v59, vcc
	v_fma_f32 v3, -v5, v2, v3
	global_store_dwordx2 v16, v[2:3], s[8:9]
	v_add_u32_e32 v16, v16, v19
	v_cndmask_b32_e32 v2, v35, v60, vcc
	v_fma_f32 v3, -v5, v2, v3
	global_store_dwordx2 v16, v[2:3], s[8:9]
	v_add_u32_e32 v16, v16, v19
	v_cndmask_b32_e32 v2, v34, v61, vcc
	v_fma_f32 v3, -v5, v2, v3
	global_store_dwordx2 v16, v[2:3], s[8:9]
	v_add_u32_e32 v16, v16, v19
	v_cndmask_b32_e32 v2, v33, v62, vcc
	v_fma_f32 v3, -v5, v2, v3
	global_store_dwordx2 v16, v[2:3], s[8:9]
	v_add_u32_e32 v16, v16, v19
	v_cndmask_b32_e32 v2, v32, v63, vcc
	v_fma_f32 v3, -v5, v2, v3
	global_store_dwordx2 v16, v[2:3], s[8:9]
